# resid epilogue: X rows of sub-tiles 1..3 touched before sub-tile 0's loads (de-serialised load ladder)
# baseline (speedup 1.0000x reference)
; template <int NT>
; __device__ __forceinline__ void gemm_compute(f32x4 (&acc)[4][NT], const bf16_t* sA, const bf16_t* sB, int wr, int wc, int fr, int fq) {
; #pragma unroll
;     for (int ks = 0; ks < 2; ++ks) {
;         bf16x8 a[4], b[NT];
; #pragma unroll
;         for (int mt = 0; mt < 4; ++mt) a[mt] = *(const bf16x8*)(sA + (wr * 64 + mt * 16 + fr) * LDT + ks * 32 + fq * 8);
; #pragma unroll
;         for (int nt = 0; nt < NT; ++nt) b[nt] = *(const bf16x8*)(sB + (wc * 16 * NT + nt * 16 + fr) * LDT + ks * 32 + fq * 8);
;         __builtin_amdgcn_s_setprio(1);
; #pragma unroll
;         for (int mt = 0; mt < 4; ++mt)
; #pragma unroll
;             for (int nt = 0; nt < NT; ++nt)
;                 acc[mt][nt] = __builtin_amdgcn_mfma_f32_16x16x32_bf16(b[nt], a[mt], acc[mt][nt], 0, 0, 0);
;         __builtin_amdgcn_s_setprio(0);
;     }
; }
; template <int NT>
; __device__ __forceinline__ void gemm_tile(f32x4 (&acc)[4][NT], const bf16_t* A, int lda, const bf16_t* B, int ldb, int K, bf16_t* sm) {
;     const int tid_ = tidx();
;     bf16_t* sA = sm; bf16_t* sB = sm + 128 * LDT;
;     const int tid = tid_, lane = tid & 63, wid = tid >> 6, wr = wid >> 1, wc = wid & 1;
;     const int fr = lane & 15, fq = lane >> 4;
;     const int lrow = tid >> 3, lkc = tid & 7;
;     const bf16_t* ga = A + (size_t)lrow * lda + lkc * 8;
;     const bf16_t* gb = B + (size_t)lrow * ldb + lkc * 8;
;     int sbrow[NT];
; #pragma unroll
;     for (int i = 0; i < NT; ++i) { const int g = lrow + 32 * i, W_ = 16 * NT, rem = g % W_; sbrow[i] = (g / W_) * W_ + (rem % NT) * 16 + rem / NT; }
;     u32x4 ra0[4], rb0[NT];
; #pragma unroll
;     for (int i = 0; i < 4; ++i) ra0[i] = *(const u32x4*)(ga + (size_t)(32 * i) * lda);
; #pragma unroll
;     for (int i = 0; i < NT; ++i) rb0[i] = *(const u32x4*)(gb + (size_t)(32 * i) * ldb);
;     const int nk = K >> 6;
;     for (int kt = 0; kt < nk; ++kt) {
;         lds_barrier();
; #pragma unroll
;         for (int i = 0; i < 4; ++i) *(u32x4*)(sA + (lrow + 32 * i) * LDT + lkc * 8) = ra0[i];
; #pragma unroll
;         for (int i = 0; i < NT; ++i) *(u32x4*)(sB + sbrow[i] * LDT + lkc * 8) = rb0[i];
;         lds_barrier();
;         if (kt + 1 < nk) {
;             ga += 64; gb += 64;
; #pragma unroll
;             for (int i = 0; i < 4; ++i) ra0[i] = *(const u32x4*)(ga + (size_t)(32 * i) * lda);
; #pragma unroll
.Lgemm_x36:
	ds_read_b128 v[160:163], v245 offset:0
	ds_read_b128 v[164:167], v245 offset:2048
	ds_read_b128 v[168:171], v245 offset:4096
	ds_read_b128 v[172:175], v245 offset:6144
	ds_read_b128 v[176:179], v247 offset:0
	ds_read_b128 v[180:183], v247 offset:2048
	ds_read_b128 v[184:187], v247 offset:4096
	ds_read_b128 v[188:191], v247 offset:6144
	s_setprio 1
	s_waitcnt lgkmcnt(11)
	v_mfma_f32_16x16x32_bf16 v[94:97], v[142:145], v[126:129], v[94:97]
	s_waitcnt lgkmcnt(10)
	v_mfma_f32_16x16x32_bf16 v[90:93], v[146:149], v[126:129], v[90:93]
	s_waitcnt lgkmcnt(9)
	v_mfma_f32_16x16x32_bf16 v[86:89], v[152:155], v[126:129], v[86:89]
	s_waitcnt lgkmcnt(8)
	v_mfma_f32_16x16x32_bf16 v[82:85], v[156:159], v[126:129], v[82:85]
	v_mfma_f32_16x16x32_bf16 v[78:81], v[142:145], v[130:133], v[78:81]
	v_mfma_f32_16x16x32_bf16 v[74:77], v[146:149], v[130:133], v[74:77]
	v_mfma_f32_16x16x32_bf16 v[70:73], v[152:155], v[130:133], v[70:73]
	v_mfma_f32_16x16x32_bf16 v[66:69], v[156:159], v[130:133], v[66:69]
	v_mfma_f32_16x16x32_bf16 v[62:65], v[142:145], v[134:137], v[62:65]
	v_mfma_f32_16x16x32_bf16 v[58:61], v[146:149], v[134:137], v[58:61]
	v_mfma_f32_16x16x32_bf16 v[54:57], v[152:155], v[134:137], v[54:57]
	v_mfma_f32_16x16x32_bf16 v[50:53], v[156:159], v[134:137], v[50:53]
	v_mfma_f32_16x16x32_bf16 v[46:49], v[142:145], v[138:141], v[46:49]
	v_mfma_f32_16x16x32_bf16 v[42:45], v[146:149], v[138:141], v[42:45]
	v_mfma_f32_16x16x32_bf16 v[38:41], v[152:155], v[138:141], v[38:41]
	v_mfma_f32_16x16x32_bf16 v[34:37], v[156:159], v[138:141], v[34:37]
	s_setprio 0
	s_waitcnt vmcnt(0) lgkmcnt(0)
	s_barrier
	ds_read_b128 v[126:129], v244 offset:32768
	ds_read_b128 v[130:133], v244 offset:34816
	ds_read_b128 v[134:137], v244 offset:36864
	ds_read_b128 v[138:141], v244 offset:38912
	ds_read_b128 v[142:145], v246 offset:32768
	ds_read_b128 v[146:149], v246 offset:34816
	ds_read_b128 v[152:155], v246 offset:36864
	ds_read_b128 v[156:159], v246 offset:38912
	s_setprio 1
	v_mfma_f32_16x16x32_bf16 v[94:97], v[176:179], v[160:163], v[94:97]
	s_lshl_b32 s95, s94, 2
	s_add_u32 m0, s95, 0x0
	s_nop 0
	global_load_lds_dwordx4 v236, s[90:91]
	v_mfma_f32_16x16x32_bf16 v[90:93], v[180:183], v[160:163], v[90:93]
	v_mfma_f32_16x16x32_bf16 v[86:89], v[184:187], v[160:163], v[86:89]
	global_load_lds_dwordx4 v237, s[90:91] offset:1024
	v_mfma_f32_16x16x32_bf16 v[82:85], v[188:191], v[160:163], v[82:85]
	v_mfma_f32_16x16x32_bf16 v[78:81], v[176:179], v[164:167], v[78:81]
	global_load_lds_dwordx4 v238, s[90:91] offset:2048
	v_mfma_f32_16x16x32_bf16 v[74:77], v[180:183], v[164:167], v[74:77]
	v_mfma_f32_16x16x32_bf16 v[70:73], v[184:187], v[164:167], v[70:73]
	global_load_lds_dwordx4 v239, s[90:91] offset:3072
	v_mfma_f32_16x16x32_bf16 v[66:69], v[188:191], v[164:167], v[66:69]
	v_mfma_f32_16x16x32_bf16 v[62:65], v[176:179], v[168:171], v[62:65]
	s_mul_i32 s95, s94, 4
	s_add_u32 m0, s95, 0x4000
	s_nop 0
	global_load_lds_dwordx4 v240, s[92:93]
	v_mfma_f32_16x16x32_bf16 v[58:61], v[180:183], v[168:171], v[58:61]
	v_mfma_f32_16x16x32_bf16 v[54:57], v[184:187], v[168:171], v[54:57]
	global_load_lds_dwordx4 v241, s[92:93] offset:1024
	v_mfma_f32_16x16x32_bf16 v[50:53], v[188:191], v[168:171], v[50:53]
	v_mfma_f32_16x16x32_bf16 v[46:49], v[176:179], v[172:175], v[46:49]
	global_load_lds_dwordx4 v242, s[92:93] offset:2048
	v_mfma_f32_16x16x32_bf16 v[42:45], v[180:183], v[172:175], v[42:45]
	v_mfma_f32_16x16x32_bf16 v[38:41], v[184:187], v[172:175], v[38:41]
	global_load_lds_dwordx4 v243, s[92:93] offset:3072
	v_mfma_f32_16x16x32_bf16 v[34:37], v[188:191], v[172:175], v[34:37]
	s_add_u32 s90, s90, 0x80
	s_addc_u32 s91, s91, 0
	s_add_u32 s92, s92, 0x80
	s_addc_u32 s93, s93, 0
	s_setprio 0
	ds_read_b128 v[160:163], v245 offset:32768
	ds_read_b128 v[164:167], v245 offset:34816
	ds_read_b128 v[168:171], v245 offset:36864
	ds_read_b128 v[172:175], v245 offset:38912
	ds_read_b128 v[176:179], v247 offset:32768
	ds_read_b128 v[180:183], v247 offset:34816
	ds_read_b128 v[184:187], v247 offset:36864
	ds_read_b128 v[188:191], v247 offset:38912
	s_setprio 1
	s_waitcnt lgkmcnt(11)
	v_mfma_f32_16x16x32_bf16 v[94:97], v[142:145], v[126:129], v[94:97]
	s_waitcnt lgkmcnt(10)
	v_mfma_f32_16x16x32_bf16 v[90:93], v[146:149], v[126:129], v[90:93]
	s_waitcnt lgkmcnt(9)
	v_mfma_f32_16x16x32_bf16 v[86:89], v[152:155], v[126:129], v[86:89]
	s_waitcnt lgkmcnt(8)
	v_mfma_f32_16x16x32_bf16 v[82:85], v[156:159], v[126:129], v[82:85]
	v_mfma_f32_16x16x32_bf16 v[78:81], v[142:145], v[130:133], v[78:81]
	v_mfma_f32_16x16x32_bf16 v[74:77], v[146:149], v[130:133], v[74:77]
	v_mfma_f32_16x16x32_bf16 v[70:73], v[152:155], v[130:133], v[70:73]
	v_mfma_f32_16x16x32_bf16 v[66:69], v[156:159], v[130:133], v[66:69]
	v_mfma_f32_16x16x32_bf16 v[62:65], v[142:145], v[134:137], v[62:65]
	v_mfma_f32_16x16x32_bf16 v[58:61], v[146:149], v[134:137], v[58:61]
	v_mfma_f32_16x16x32_bf16 v[54:57], v[152:155], v[134:137], v[54:57]
	v_mfma_f32_16x16x32_bf16 v[50:53], v[156:159], v[134:137], v[50:53]
	v_mfma_f32_16x16x32_bf16 v[46:49], v[142:145], v[138:141], v[46:49]
	v_mfma_f32_16x16x32_bf16 v[42:45], v[146:149], v[138:141], v[42:45]
	v_mfma_f32_16x16x32_bf16 v[38:41], v[152:155], v[138:141], v[38:41]
	v_mfma_f32_16x16x32_bf16 v[34:37], v[156:159], v[138:141], v[34:37]
	s_setprio 0
	s_waitcnt vmcnt(0) lgkmcnt(0)
	s_barrier
; template <int NT>
; __device__ __forceinline__ void gemm_compute(f32x4 (&acc)[4][NT], const bf16_t* sA, const bf16_t* sB, int wr, int wc, int fr, int fq) {
; #pragma unroll
;     for (int ks = 0; ks < 2; ++ks) {
;         bf16x8 a[4], b[NT];
; #pragma unroll
;         for (int mt = 0; mt < 4; ++mt) a[mt] = *(const bf16x8*)(sA + (wr * 64 + mt * 16 + fr) * LDT + ks * 32 + fq * 8);
; #pragma unroll
;         for (int nt = 0; nt < NT; ++nt) b[nt] = *(const bf16x8*)(sB + (wc * 16 * NT + nt * 16 + fr) * LDT + ks * 32 + fq * 8);
;         __builtin_amdgcn_s_setprio(1);
; #pragma unroll
;         for (int mt = 0; mt < 4; ++mt)
; #pragma unroll
;             for (int nt = 0; nt < NT; ++nt)
;                 acc[mt][nt] = __builtin_amdgcn_mfma_f32_16x16x32_bf16(b[nt], a[mt], acc[mt][nt], 0, 0, 0);
;         __builtin_amdgcn_s_setprio(0);
;     }
; }
; template <int NT>
; __device__ __forceinline__ void gemm_tile(f32x4 (&acc)[4][NT], const bf16_t* A, int lda, const bf16_t* B, int ldb, int K, bf16_t* sm) {
;     ...
;     for (int kt = 0; kt < nk; ++kt) {
;         lds_barrier();
; #pragma unroll
;         for (int i = 0; i < 4; ++i) *(u32x4*)(sA + (lrow + 32 * i) * LDT + lkc * 8) = ra0[i];
; #pragma unroll
;         for (int i = 0; i < NT; ++i) *(u32x4*)(sB + sbrow[i] * LDT + lkc * 8) = rb0[i];
;         lds_barrier();
;         if (kt + 1 < nk) {
;             ga += 64; gb += 64;
; #pragma unroll
;             for (int i = 0; i < 4; ++i) ra0[i] = *(const u32x4*)(ga + (size_t)(32 * i) * lda);
; #pragma unroll
;             for (int i = 0; i < NT; ++i) rb0[i] = *(const u32x4*)(gb + (size_t)(32 * i) * ldb);
;         }
;         __builtin_amdgcn_sched_barrier(0);
;         gemm_compute<NT>(acc, sA, sB, wr, wc, fr, fq);
	ds_read_b128 v[126:129], v244 offset:0
	ds_read_b128 v[130:133], v244 offset:2048
	ds_read_b128 v[134:137], v244 offset:4096
	ds_read_b128 v[138:141], v244 offset:6144
	ds_read_b128 v[142:145], v246 offset:0
	ds_read_b128 v[146:149], v246 offset:2048
	ds_read_b128 v[152:155], v246 offset:4096
	ds_read_b128 v[156:159], v246 offset:6144
	s_setprio 1
	v_mfma_f32_16x16x32_bf16 v[94:97], v[176:179], v[160:163], v[94:97]
	s_lshl_b32 s92, s96, 1
	s_sub_u32 s92, s92, 0x100
	s_mov_b32 s93, 0
	v_lshl_add_u64 v[102:103], v[102:103], 0, s[92:93]
	v_lshl_add_u64 v[104:105], v[104:105], 0, s[92:93]
	v_lshl_add_u64 v[106:107], v[106:107], 0, s[92:93]
	v_lshl_add_u64 v[108:109], v[108:109], 0, s[92:93]
	v_lshl_add_u64 v[110:111], v[110:111], 0, s[92:93]
	v_lshl_add_u64 v[112:113], v[112:113], 0, s[92:93]
	v_lshl_add_u64 v[114:115], v[114:115], 0, s[92:93]
	v_lshl_add_u64 v[116:117], v[116:117], 0, s[92:93]
	v_readlane_b32 s90, v234, 0
	v_readlane_b32 s91, v234, 1
	v_readlane_b32 s92, v234, 2
	v_readlane_b32 s93, v234, 3
	v_readlane_b32 s94, v234, 4
	v_readlane_b32 s95, v234, 5
	s_mov_b32 s19, 0
	s_nop 3
	v_mfma_f32_16x16x32_bf16 v[90:93], v[180:183], v[160:163], v[90:93]
	v_mfma_f32_16x16x32_bf16 v[86:89], v[184:187], v[160:163], v[86:89]
	v_lshl_add_u64 v[0:1], v[108:109], 0, v[100:101]
	v_mfma_f32_16x16x32_bf16 v[82:85], v[188:191], v[160:163], v[82:85]
	v_mfma_f32_16x16x32_bf16 v[78:81], v[176:179], v[164:167], v[78:81]
	global_load_dwordx4 v[30:33], v[0:1], off
	v_mfma_f32_16x16x32_bf16 v[74:77], v[180:183], v[164:167], v[74:77]
	v_mfma_f32_16x16x32_bf16 v[70:73], v[184:187], v[164:167], v[70:73]
	v_lshl_add_u64 v[0:1], v[106:107], 0, v[100:101]
	v_mfma_f32_16x16x32_bf16 v[66:69], v[188:191], v[164:167], v[66:69]
	v_mfma_f32_16x16x32_bf16 v[62:65], v[176:179], v[168:171], v[62:65]
	global_load_dwordx4 v[22:25], v[0:1], off
	v_mfma_f32_16x16x32_bf16 v[58:61], v[180:183], v[168:171], v[58:61]
	v_mfma_f32_16x16x32_bf16 v[54:57], v[184:187], v[168:171], v[54:57]
	v_lshl_add_u64 v[0:1], v[104:105], 0, v[100:101]
	v_mfma_f32_16x16x32_bf16 v[50:53], v[188:191], v[168:171], v[50:53]
	v_mfma_f32_16x16x32_bf16 v[46:49], v[176:179], v[172:175], v[46:49]
	global_load_dwordx4 v[18:21], v[0:1], off
	v_mfma_f32_16x16x32_bf16 v[42:45], v[180:183], v[172:175], v[42:45]
	v_mfma_f32_16x16x32_bf16 v[38:41], v[184:187], v[172:175], v[38:41]
	v_lshl_add_u64 v[0:1], v[102:103], 0, v[100:101]
	v_mfma_f32_16x16x32_bf16 v[34:37], v[188:191], v[172:175], v[34:37]
	global_load_dwordx4 v[26:29], v[0:1], off
	v_lshl_add_u64 v[0:1], v[116:117], 0, v[100:101]
	global_load_dwordx4 v[8:11], v[0:1], off
	v_lshl_add_u64 v[0:1], v[114:115], 0, v[100:101]
	v_lshl_add_u64 v[4:5], v[112:113], 0, v[100:101]
	v_lshl_add_u64 v[14:15], v[110:111], 0, v[100:101]
	global_load_dwordx4 v[0:3], v[0:1], off
	s_nop 0
	global_load_dwordx4 v[4:7], v[4:5], off
	s_nop 0
	global_load_dwordx4 v[14:17], v[14:15], off
	s_setprio 0
	ds_read_b128 v[160:163], v245 offset:0
	ds_read_b128 v[164:167], v245 offset:2048
	ds_read_b128 v[168:171], v245 offset:4096
	ds_read_b128 v[172:175], v245 offset:6144
	ds_read_b128 v[176:179], v247 offset:0
	ds_read_b128 v[180:183], v247 offset:2048
	ds_read_b128 v[184:187], v247 offset:4096
	ds_read_b128 v[188:191], v247 offset:6144
	s_setprio 1
	s_waitcnt lgkmcnt(11)
	v_mfma_f32_16x16x32_bf16 v[94:97], v[142:145], v[126:129], v[94:97]
	s_waitcnt lgkmcnt(10)
	v_mfma_f32_16x16x32_bf16 v[90:93], v[146:149], v[126:129], v[90:93]
	s_waitcnt lgkmcnt(9)
	v_mfma_f32_16x16x32_bf16 v[86:89], v[152:155], v[126:129], v[86:89]
	s_waitcnt lgkmcnt(8)
	v_mfma_f32_16x16x32_bf16 v[82:85], v[156:159], v[126:129], v[82:85]
	v_mfma_f32_16x16x32_bf16 v[78:81], v[142:145], v[130:133], v[78:81]
	v_mfma_f32_16x16x32_bf16 v[74:77], v[146:149], v[130:133], v[74:77]
	v_mfma_f32_16x16x32_bf16 v[70:73], v[152:155], v[130:133], v[70:73]
	v_mfma_f32_16x16x32_bf16 v[66:69], v[156:159], v[130:133], v[66:69]
	v_mfma_f32_16x16x32_bf16 v[62:65], v[142:145], v[134:137], v[62:65]
	v_mfma_f32_16x16x32_bf16 v[58:61], v[146:149], v[134:137], v[58:61]
	v_mfma_f32_16x16x32_bf16 v[54:57], v[152:155], v[134:137], v[54:57]
	v_mfma_f32_16x16x32_bf16 v[50:53], v[156:159], v[134:137], v[50:53]
	v_mfma_f32_16x16x32_bf16 v[46:49], v[142:145], v[138:141], v[46:49]
	v_mfma_f32_16x16x32_bf16 v[42:45], v[146:149], v[138:141], v[42:45]
	v_mfma_f32_16x16x32_bf16 v[38:41], v[152:155], v[138:141], v[38:41]
	v_mfma_f32_16x16x32_bf16 v[34:37], v[156:159], v[138:141], v[34:37]
	s_setprio 0
	s_waitcnt lgkmcnt(0)
	s_setprio 1
	v_mfma_f32_16x16x32_bf16 v[94:97], v[176:179], v[160:163], v[94:97]
	v_mfma_f32_16x16x32_bf16 v[90:93], v[180:183], v[160:163], v[90:93]
	v_mfma_f32_16x16x32_bf16 v[86:89], v[184:187], v[160:163], v[86:89]
	v_mfma_f32_16x16x32_bf16 v[82:85], v[188:191], v[160:163], v[82:85]
	v_mfma_f32_16x16x32_bf16 v[78:81], v[176:179], v[164:167], v[78:81]
	v_mfma_f32_16x16x32_bf16 v[74:77], v[180:183], v[164:167], v[74:77]
	v_mfma_f32_16x16x32_bf16 v[70:73], v[184:187], v[164:167], v[70:73]
	v_mfma_f32_16x16x32_bf16 v[66:69], v[188:191], v[164:167], v[66:69]
	v_mfma_f32_16x16x32_bf16 v[62:65], v[176:179], v[168:171], v[62:65]
	v_mfma_f32_16x16x32_bf16 v[58:61], v[180:183], v[168:171], v[58:61]
	v_mfma_f32_16x16x32_bf16 v[54:57], v[184:187], v[168:171], v[54:57]
	v_mfma_f32_16x16x32_bf16 v[50:53], v[188:191], v[168:171], v[50:53]
	v_mfma_f32_16x16x32_bf16 v[46:49], v[176:179], v[172:175], v[46:49]
	v_mfma_f32_16x16x32_bf16 v[42:45], v[180:183], v[172:175], v[42:45]
	v_mfma_f32_16x16x32_bf16 v[38:41], v[184:187], v[172:175], v[38:41]
	v_mfma_f32_16x16x32_bf16 v[34:37], v[188:191], v[172:175], v[34:37]
	s_setprio 0
	s_waitcnt lgkmcnt(0)
	s_barrier
; template <int NT>
; __device__ __forceinline__ void gemm_compute(f32x4 (&acc)[4][NT], const bf16_t* sA, const bf16_t* sB, int wr, int wc, int fr, int fq) {
; #pragma unroll
;     for (int ks = 0; ks < 2; ++ks) {
;         bf16x8 a[4], b[NT];
; #pragma unroll
;         for (int mt = 0; mt < 4; ++mt) a[mt] = *(const bf16x8*)(sA + (wr * 64 + mt * 16 + fr) * LDT + ks * 32 + fq * 8);
; #pragma unroll
;         for (int nt = 0; nt < NT; ++nt) b[nt] = *(const bf16x8*)(sB + (wc * 16 * NT + nt * 16 + fr) * LDT + ks * 32 + fq * 8);
;         __builtin_amdgcn_s_setprio(1);
; #pragma unroll
;         for (int mt = 0; mt < 4; ++mt)
; #pragma unroll
;             for (int nt = 0; nt < NT; ++nt)
;                 acc[mt][nt] = __builtin_amdgcn_mfma_f32_16x16x32_bf16(b[nt], a[mt], acc[mt][nt], 0, 0, 0);
;         __builtin_amdgcn_s_setprio(0);
;     }
; }
; template <int NT>
; __device__ __forceinline__ void resid_tile(int tm, int col0, const bf16_t* A, int lda, int K, const bf16_t* W, const float* X, float* Y, float scale, bf16_t* sm) {
;     ...
;     gemm_tile<NT>(acc, A + (size_t)tm * 128 * lda, lda, W + (size_t)col0 * K, K, K, sm);
; #pragma unroll
;     for (int mt = 0; mt < 4; ++mt) {
;         const int row = tm * 128 + wr * 64 + mt * 16 + fr;
;         const int cbase = col0 + wc * 16 * NT + fq * 4 * NT;
;         const size_t o = (size_t)row * 1024 + cbase;
;         float v[4 * NT]; gather_cols<NT>(acc, mt, v);
;         float4 xv[NT];
; #pragma unroll
;         for (int q = 0; q < NT; ++q) xv[q] = *(const float4*)(X + o + 4 * q);
; #pragma unroll
;         for (int q = 0; q < NT; ++q)
;             *(float4*)(Y + o + 4 * q) = make_float4(ALPHA * xv[q].x + scale * v[4 * q], ALPHA * xv[q].y + scale * v[4 * q + 1],
;                                                     ALPHA * xv[q].z + scale * v[4 * q + 2], ALPHA * xv[q].w + scale * v[4 * q + 3]);
	s_waitcnt vmcnt(7)
	ds_write_b128 v120, v[30:33]
	s_waitcnt vmcnt(6)
	ds_write_b128 v120, v[22:25] offset:5120
	s_waitcnt vmcnt(5)
	ds_write_b128 v120, v[18:21] offset:10240
	s_waitcnt vmcnt(4)
	ds_write_b128 v120, v[26:29] offset:15360
	s_waitcnt vmcnt(3)
	ds_write_b128 v121, v[8:11] offset:20480
	s_waitcnt vmcnt(2)
	ds_write_b128 v122, v[0:3] offset:20480
	s_waitcnt vmcnt(1)
	ds_write_b128 v123, v[4:7] offset:20480
	s_waitcnt vmcnt(0)
	ds_write_b128 v124, v[14:17] offset:20480
	s_waitcnt lgkmcnt(0)
	s_barrier
	ds_read_b128 v[0:3], v119
	ds_read_b128 v[4:7], v119 offset:2560
	ds_read_b128 v[8:11], v119 offset:5120
	ds_read_b128 v[14:17], v119 offset:7680
	ds_read_b128 v[18:21], v12 offset:20480
	ds_read_b128 v[22:25], v12 offset:23040
	ds_read_b128 v[26:29], v12 offset:25600
	ds_read_b128 v[30:33], v12 offset:28160
	s_setprio 1
	s_waitcnt lgkmcnt(3)
	v_mfma_f32_16x16x32_bf16 v[94:97], v[18:21], v[0:3], v[94:97]
	s_waitcnt lgkmcnt(2)
	v_mfma_f32_16x16x32_bf16 v[90:93], v[22:25], v[0:3], v[90:93]
	s_waitcnt lgkmcnt(1)
	v_mfma_f32_16x16x32_bf16 v[86:89], v[26:29], v[0:3], v[86:89]
	s_waitcnt lgkmcnt(0)
	v_mfma_f32_16x16x32_bf16 v[0:3], v[30:33], v[0:3], v[82:85]
	v_mfma_f32_16x16x32_bf16 v[78:81], v[18:21], v[4:7], v[78:81]
	v_mfma_f32_16x16x32_bf16 v[74:77], v[22:25], v[4:7], v[74:77]
	v_mfma_f32_16x16x32_bf16 v[70:73], v[26:29], v[4:7], v[70:73]
	v_mfma_f32_16x16x32_bf16 v[4:7], v[30:33], v[4:7], v[66:69]
	v_mfma_f32_16x16x32_bf16 v[62:65], v[18:21], v[8:11], v[62:65]
	v_mfma_f32_16x16x32_bf16 v[58:61], v[22:25], v[8:11], v[58:61]
	v_mfma_f32_16x16x32_bf16 v[54:57], v[26:29], v[8:11], v[54:57]
	v_mfma_f32_16x16x32_bf16 v[8:11], v[30:33], v[8:11], v[50:53]
	v_mfma_f32_16x16x32_bf16 v[50:53], v[18:21], v[14:17], v[46:49]
	v_mfma_f32_16x16x32_bf16 v[66:69], v[22:25], v[14:17], v[42:45]
	v_mfma_f32_16x16x32_bf16 v[82:85], v[26:29], v[14:17], v[38:41]
	v_mfma_f32_16x16x32_bf16 v[100:103], v[30:33], v[14:17], v[34:37]
	s_setprio 0
	ds_read_b128 v[14:17], v119 offset:64
	ds_read_b128 v[18:21], v119 offset:2624
	ds_read_b128 v[22:25], v119 offset:5184
	ds_read_b128 v[104:107], v119 offset:7744
	ds_read_b128 v[108:111], v12 offset:20544
	ds_read_b128 v[112:115], v12 offset:23104
	ds_read_b128 v[120:123], v12 offset:25664
	ds_read_b128 v[124:127], v12 offset:28224
	s_setprio 1
	s_waitcnt lgkmcnt(3)
	v_mfma_f32_16x16x32_bf16 v[94:97], v[108:111], v[14:17], v[94:97]
	s_waitcnt lgkmcnt(2)
	v_mfma_f32_16x16x32_bf16 v[90:93], v[112:115], v[14:17], v[90:93]
	s_waitcnt lgkmcnt(1)
	v_mfma_f32_16x16x32_bf16 v[86:89], v[120:123], v[14:17], v[86:89]
	s_waitcnt lgkmcnt(0)
	v_mfma_f32_16x16x32_bf16 v[128:131], v[124:127], v[14:17], v[0:3]
	v_mfma_f32_16x16x32_bf16 v[42:45], v[108:111], v[18:21], v[78:81]
	v_mfma_f32_16x16x32_bf16 v[46:49], v[112:115], v[18:21], v[74:77]
	v_mfma_f32_16x16x32_bf16 v[34:37], v[120:123], v[18:21], v[70:73]
	v_mfma_f32_16x16x32_bf16 v[38:41], v[124:127], v[18:21], v[4:7]
	v_mfma_f32_16x16x32_bf16 v[26:29], v[108:111], v[22:25], v[62:65]
	v_mfma_f32_16x16x32_bf16 v[30:33], v[112:115], v[22:25], v[58:61]
	v_mfma_f32_16x16x32_bf16 v[18:21], v[120:123], v[22:25], v[54:57]
	v_mfma_f32_16x16x32_bf16 v[22:25], v[124:127], v[22:25], v[8:11]
	v_mfma_f32_16x16x32_bf16 v[8:11], v[108:111], v[104:107], v[50:53]
	v_mfma_f32_16x16x32_bf16 v[14:17], v[112:115], v[104:107], v[66:69]
	v_mfma_f32_16x16x32_bf16 v[0:3], v[120:123], v[104:107], v[82:85]
	v_mfma_f32_16x16x32_bf16 v[4:7], v[124:127], v[104:107], v[100:103]
	s_setprio 0
	v_ashrrev_i32_e32 v12, 1, v118
	v_and_b32_e32 v12, 0xffffffc0, v12
	v_lshl_add_u32 v12, s18, 7, v12
	v_and_or_b32 v50, v118, 15, v12
	v_and_b32_e32 v12, 0x70, v118
	v_or_b32_e32 v12, s2, v12
	v_ashrrev_i32_e32 v51, 31, v50
	v_lshlrev_b64 v[52:53], 12, v[50:51]
	v_lshlrev_b32_e32 v12, 2, v12
	v_or_b32_e32 v52, v52, v12
	v_lshl_add_u64 v[64:65], s[56:57], 0, v[52:53]
	v_lshl_add_u64 v[68:69], s[90:91], 0, v[52:53]
	v_or_b32_e32 v160, 16, v50
	v_mov_b32_e32 v161, 0
	v_lshlrev_b64 v[160:161], 12, v[160:161]
	v_or_b32_e32 v160, v160, v12
	v_lshl_add_u64 v[160:161], s[56:57], 0, v[160:161]
	global_load_dword v162, v[160:161], off
	v_or_b32_e32 v160, 32, v50
	v_mov_b32_e32 v161, 0
	v_lshlrev_b64 v[160:161], 12, v[160:161]
	v_or_b32_e32 v160, v160, v12
	v_lshl_add_u64 v[160:161], s[56:57], 0, v[160:161]
	global_load_dword v163, v[160:161], off
	v_or_b32_e32 v160, 48, v50
	v_mov_b32_e32 v161, 0
	v_lshlrev_b64 v[160:161], 12, v[160:161]
	v_or_b32_e32 v160, v160, v12
	v_lshl_add_u64 v[160:161], s[56:57], 0, v[160:161]
	global_load_dword v164, v[160:161], off
	global_load_dwordx4 v[52:55], v[64:65], off offset:48
	global_load_dwordx4 v[56:59], v[64:65], off offset:32
	global_load_dwordx4 v[60:63], v[64:65], off offset:16
	s_nop 0
	global_load_dwordx4 v[64:67], v[64:65], off
	v_mov_b32_e32 v70, v94
	v_mov_b32_e32 v71, v90
	v_mov_b32_e32 v90, v95
	s_add_i32 s39, s39, s62
	s_cmp_ge_i32 s39, s1
	s_waitcnt vmcnt(3)
	v_pk_mul_f32 v[52:53], v[52:53], s[88:89] op_sel_hi:[1,0]
	s_waitcnt vmcnt(2)
	v_pk_mul_f32 v[56:57], v[56:57], s[88:89] op_sel_hi:[1,0]
	s_waitcnt vmcnt(1)
	v_pk_mul_f32 v[60:61], v[60:61], s[88:89] op_sel_hi:[1,0]
	s_waitcnt vmcnt(0)
; template <int NT>
; __device__ __forceinline__ void resid_tile(int tm, int col0, const bf16_t* A, int lda, int K, const bf16_t* W, const float* X, float* Y, float scale, bf16_t* sm) {
;     ...
; #pragma unroll
;     for (int mt = 0; mt < 4; ++mt) {
;         const int row = tm * 128 + wr * 64 + mt * 16 + fr;
;         const int cbase = col0 + wc * 16 * NT + fq * 4 * NT;
;         const size_t o = (size_t)row * 1024 + cbase;
;         float v[4 * NT]; gather_cols<NT>(acc, mt, v);
;         float4 xv[NT];
; #pragma unroll
;         for (int q = 0; q < NT; ++q) xv[q] = *(const float4*)(X + o + 4 * q);
; #pragma unroll
;         for (int q = 0; q < NT; ++q)
;             *(float4*)(Y + o + 4 * q) = make_float4(ALPHA * xv[q].x + scale * v[4 * q], ALPHA * xv[q].y + scale * v[4 * q + 1],
;                                                     ALPHA * xv[q].z + scale * v[4 * q + 2], ALPHA * xv[q].w + scale * v[4 * q + 3]);
;     }
; }
; __device__ __forceinline__ void phase_gemm_resid(const bf16_t* A, int lda, int K, const bf16_t* W, const float* X, float* Y, float scale, bf16_t* sm) {
;     const int G = gridDim.x, NTILES = 136 * 8;
;     const int nfull = (NTILES / G) * G;
;     for (int t = blockIdx.x; t < nfull; t += G) resid_tile<4>(t >> 3, (t & 7) * 128, A, lda, K, W, X, Y, scale, sm);
	v_pk_mul_f32 v[64:65], v[64:65], s[88:89] op_sel_hi:[1,0]
	v_pk_mul_f32 v[66:67], v[66:67], s[88:89] op_sel_hi:[1,0]
	v_pk_fma_f32 v[64:65], v[98:99], v[70:71], v[64:65]
	v_mov_b32_e32 v70, v86
	v_mov_b32_e32 v71, v128
	v_pk_fma_f32 v[66:67], v[98:99], v[70:71], v[66:67]
	v_mov_b32_e32 v70, v96
	v_mov_b32_e32 v71, v92
	v_mov_b32_e32 v92, v97
	v_pk_mul_f32 v[62:63], v[62:63], s[88:89] op_sel_hi:[1,0]
	v_mov_b32_e32 v128, v87
	v_pk_fma_f32 v[56:57], v[98:99], v[70:71], v[56:57]
	v_pk_mul_f32 v[58:59], v[58:59], s[88:89] op_sel_hi:[1,0]
	v_mov_b32_e32 v70, v88
	v_mov_b32_e32 v71, v130
	v_pk_fma_f32 v[52:53], v[98:99], v[92:93], v[52:53]
	v_pk_mul_f32 v[54:55], v[54:55], s[88:89] op_sel_hi:[1,0]
	v_mov_b32_e32 v130, v89
	v_pk_fma_f32 v[60:61], v[98:99], v[90:91], v[60:61]
	v_pk_fma_f32 v[62:63], v[98:99], v[128:129], v[62:63]
	v_pk_fma_f32 v[58:59], v[98:99], v[70:71], v[58:59]
	v_pk_fma_f32 v[54:55], v[98:99], v[130:131], v[54:55]
	global_store_dwordx4 v[68:69], v[64:67], off
	global_store_dwordx4 v[68:69], v[60:63], off offset:16
	global_store_dwordx4 v[68:69], v[56:59], off offset:32
	global_store_dwordx4 v[68:69], v[52:55], off offset:48
	v_mov_b32_e32 v70, v42
	v_mov_b32_e32 v71, v46
	v_or_b32_e32 v52, 16, v50
	v_ashrrev_i32_e32 v53, 31, v52
	v_lshlrev_b64 v[52:53], 12, v[52:53]
	v_or_b32_e32 v52, v52, v12
	v_lshl_add_u64 v[64:65], s[56:57], 0, v[52:53]
	v_lshl_add_u64 v[68:69], s[90:91], 0, v[52:53]
	global_load_dwordx4 v[52:55], v[64:65], off offset:48
	global_load_dwordx4 v[56:59], v[64:65], off offset:32
	global_load_dwordx4 v[60:63], v[64:65], off offset:16
	s_nop 0
	global_load_dwordx4 v[64:67], v[64:65], off
	v_mov_b32_e32 v46, v43
	s_waitcnt vmcnt(1)
	v_pk_mul_f32 v[42:43], v[62:63], s[88:89] op_sel_hi:[1,0]
	s_waitcnt vmcnt(0)
	v_pk_mul_f32 v[64:65], v[64:65], s[88:89] op_sel_hi:[1,0]
	v_pk_mul_f32 v[66:67], v[66:67], s[88:89] op_sel_hi:[1,0]
	v_pk_fma_f32 v[64:65], v[98:99], v[70:71], v[64:65]
	v_mov_b32_e32 v71, v38
	v_mov_b32_e32 v38, v35
	v_mov_b32_e32 v70, v34
	v_pk_fma_f32 v[62:63], v[98:99], v[38:39], v[42:43]
	v_pk_mul_f32 v[34:35], v[56:57], s[88:89] op_sel_hi:[1,0]
	v_mov_b32_e32 v38, v44
	v_mov_b32_e32 v39, v48
	v_pk_fma_f32 v[56:57], v[98:99], v[38:39], v[34:35]
	v_pk_mul_f32 v[34:35], v[58:59], s[88:89] op_sel_hi:[1,0]
	v_mov_b32_e32 v38, v36
	v_mov_b32_e32 v39, v40
	v_pk_fma_f32 v[58:59], v[98:99], v[38:39], v[34:35]
	v_pk_mul_f32 v[34:35], v[52:53], s[88:89] op_sel_hi:[1,0]
	v_mov_b32_e32 v48, v45
	v_pk_fma_f32 v[66:67], v[98:99], v[70:71], v[66:67]
	v_pk_mul_f32 v[60:61], v[60:61], s[88:89] op_sel_hi:[1,0]
	v_pk_fma_f32 v[34:35], v[98:99], v[48:49], v[34:35]
	v_pk_mul_f32 v[38:39], v[54:55], s[88:89] op_sel_hi:[1,0]
	v_mov_b32_e32 v40, v37
	v_pk_fma_f32 v[60:61], v[98:99], v[46:47], v[60:61]
	v_pk_fma_f32 v[36:37], v[98:99], v[40:41], v[38:39]
	global_store_dwordx4 v[68:69], v[64:67], off
	global_store_dwordx4 v[68:69], v[60:63], off offset:16
	global_store_dwordx4 v[68:69], v[56:59], off offset:32
	global_store_dwordx4 v[68:69], v[34:37], off offset:48
	v_mov_b32_e32 v54, v26
	v_mov_b32_e32 v55, v30
	v_or_b32_e32 v34, 32, v50
	v_ashrrev_i32_e32 v35, 31, v34
	v_lshlrev_b64 v[34:35], 12, v[34:35]
	v_or_b32_e32 v34, v34, v12
	v_lshl_add_u64 v[46:47], s[56:57], 0, v[34:35]
	v_lshl_add_u64 v[52:53], s[90:91], 0, v[34:35]
	global_load_dwordx4 v[34:37], v[46:47], off offset:48
	global_load_dwordx4 v[38:41], v[46:47], off offset:32
	global_load_dwordx4 v[42:45], v[46:47], off offset:16
	s_nop 0
	global_load_dwordx4 v[46:49], v[46:47], off
	v_mov_b32_e32 v30, v27
	s_waitcnt vmcnt(1)
	v_pk_mul_f32 v[26:27], v[44:45], s[88:89] op_sel_hi:[1,0]
	s_waitcnt vmcnt(0)
	v_pk_mul_f32 v[46:47], v[46:47], s[88:89] op_sel_hi:[1,0]
	v_pk_mul_f32 v[48:49], v[48:49], s[88:89] op_sel_hi:[1,0]
	v_pk_fma_f32 v[46:47], v[98:99], v[54:55], v[46:47]
	v_mov_b32_e32 v55, v22
	v_mov_b32_e32 v22, v19
	v_mov_b32_e32 v54, v18
	v_pk_fma_f32 v[44:45], v[98:99], v[22:23], v[26:27]
	v_pk_mul_f32 v[18:19], v[38:39], s[88:89] op_sel_hi:[1,0]
	v_mov_b32_e32 v22, v28
	v_mov_b32_e32 v23, v32
	v_pk_fma_f32 v[38:39], v[98:99], v[22:23], v[18:19]
	v_pk_mul_f32 v[18:19], v[40:41], s[88:89] op_sel_hi:[1,0]
	v_mov_b32_e32 v22, v20
	v_mov_b32_e32 v23, v24
	v_pk_fma_f32 v[40:41], v[98:99], v[22:23], v[18:19]
	v_pk_mul_f32 v[18:19], v[34:35], s[88:89] op_sel_hi:[1,0]
	v_mov_b32_e32 v32, v29
	v_pk_fma_f32 v[48:49], v[98:99], v[54:55], v[48:49]
	v_pk_mul_f32 v[42:43], v[42:43], s[88:89] op_sel_hi:[1,0]
	v_pk_fma_f32 v[18:19], v[98:99], v[32:33], v[18:19]
	v_pk_mul_f32 v[22:23], v[36:37], s[88:89] op_sel_hi:[1,0]
	v_mov_b32_e32 v24, v21
	v_pk_fma_f32 v[42:43], v[98:99], v[30:31], v[42:43]
	v_pk_fma_f32 v[20:21], v[98:99], v[24:25], v[22:23]
	global_store_dwordx4 v[52:53], v[46:49], off
	global_store_dwordx4 v[52:53], v[42:45], off offset:16
	global_store_dwordx4 v[52:53], v[38:41], off offset:32
	global_store_dwordx4 v[52:53], v[18:21], off offset:48
	v_mov_b32_e32 v36, v8
	v_mov_b32_e32 v37, v14
	v_or_b32_e32 v18, 48, v50
	v_ashrrev_i32_e32 v19, 31, v18
	v_lshlrev_b64 v[18:19], 12, v[18:19]
	v_or_b32_e32 v18, v18, v12
	v_lshl_add_u64 v[30:31], s[56:57], 0, v[18:19]
	v_lshl_add_u64 v[34:35], s[90:91], 0, v[18:19]
	global_load_dwordx4 v[18:21], v[30:31], off offset:48
	global_load_dwordx4 v[22:25], v[30:31], off offset:32
	global_load_dwordx4 v[26:29], v[30:31], off offset:16
	s_nop 0
	global_load_dwordx4 v[30:33], v[30:31], off
	v_mov_b32_e32 v14, v9
	s_waitcnt vmcnt(1)
	v_pk_mul_f32 v[8:9], v[28:29], s[88:89] op_sel_hi:[1,0]
	s_waitcnt vmcnt(0)
	v_pk_mul_f32 v[30:31], v[30:31], s[88:89] op_sel_hi:[1,0]
	v_pk_mul_f32 v[32:33], v[32:33], s[88:89] op_sel_hi:[1,0]
	v_pk_fma_f32 v[30:31], v[98:99], v[36:37], v[30:31]
	v_mov_b32_e32 v37, v4
	v_mov_b32_e32 v4, v1
	v_mov_b32_e32 v36, v0
	v_pk_fma_f32 v[28:29], v[98:99], v[4:5], v[8:9]
	v_pk_mul_f32 v[0:1], v[22:23], s[88:89] op_sel_hi:[1,0]
	v_mov_b32_e32 v4, v10
	v_mov_b32_e32 v5, v16
	v_pk_fma_f32 v[22:23], v[98:99], v[4:5], v[0:1]
	v_pk_mul_f32 v[0:1], v[24:25], s[88:89] op_sel_hi:[1,0]
	v_mov_b32_e32 v4, v2
	v_mov_b32_e32 v5, v6
	v_pk_fma_f32 v[32:33], v[98:99], v[36:37], v[32:33]
	v_pk_mul_f32 v[26:27], v[26:27], s[88:89] op_sel_hi:[1,0]
	v_pk_fma_f32 v[24:25], v[98:99], v[4:5], v[0:1]
	v_pk_mul_f32 v[0:1], v[18:19], s[88:89] op_sel_hi:[1,0]
	v_mov_b32_e32 v16, v11
	v_pk_mul_f32 v[4:5], v[20:21], s[88:89] op_sel_hi:[1,0]
	v_mov_b32_e32 v6, v3
	v_pk_fma_f32 v[26:27], v[98:99], v[14:15], v[26:27]
	v_pk_fma_f32 v[0:1], v[98:99], v[16:17], v[0:1]
	v_pk_fma_f32 v[2:3], v[98:99], v[6:7], v[4:5]
	global_store_dwordx4 v[34:35], v[30:33], off
	global_store_dwordx4 v[34:35], v[26:29], off offset:16
	global_store_dwordx4 v[34:35], v[22:25], off offset:32
	global_store_dwordx4 v[34:35], v[0:3], off offset:48
	s_cbranch_scc0 .LBB0_35
